# P6: MiniGate gate loads issued together + no L2 writeback/invalidate between the two branch GEMMs; P5: inter-chunk q.C loop unrolled with 16 operand loads in flight
# speedup vs baseline: 1.0302x; 1.0302x over previous
; #define MFMA32(a, b, c) __builtin_amdgcn_mfma_f32_32x32x16_bf16((a), (b), (c), 0, 0, 0)
;     __device__ __forceinline__ bf16* DC() const { return (bf16*)(ws + WS_XN); }
; template <bool SAMPLE>
; __device__ __forceinline__ void mout_task(Ctx& C, int l, int unit, int h, int tb, const LAS float* cwl, const LAS float* gainl, LAS float* gsbuf, LAS s16x8* qfl, const bool st) {
;     ...
;         const bf16* cp = C.DC() + (size_t)slot * 16384 + (size_t)r * 128 + 8 * hi;
; #pragma unroll 1
;         for (int ks = 0; ks < 8; ++ks) { const s16x8 qv = qfl[ks * 64 + lane];
; #pragma unroll
;             for (int vb = 0; vb < 4; ++vb) acc[vb] = MFMA32(*(const s16x8*)(cp + (size_t)vb * 4096 + 16 * ks), qv, acc[vb]); }
.LBB0_907:
	s_mov_b32 s37, 0x18c00000
	v_add_co_u32_e32 v186, vcc, s37, v66
	s_nop 1
	v_addc_co_u32_e32 v187, vcc, 0, v67, vcc
	s_mov_b32 s37, 0x18c02000
	v_add_co_u32_e32 v188, vcc, s37, v66
	s_nop 1
	v_addc_co_u32_e32 v189, vcc, 0, v67, vcc
	s_mov_b32 s37, 0x18c04000
	v_add_co_u32_e32 v190, vcc, s37, v66
	s_nop 1
	v_addc_co_u32_e32 v191, vcc, 0, v67, vcc
	s_mov_b32 s37, 0x18c06000
	v_add_co_u32_e32 v194, vcc, s37, v66
	s_nop 1
	v_addc_co_u32_e32 v195, vcc, 0, v67, vcc
	global_load_dwordx4 v[88:91], v[186:187], off
	global_load_dwordx4 v[92:95], v[188:189], off
	global_load_dwordx4 v[96:99], v[190:191], off
	global_load_dwordx4 v[100:103], v[194:195], off
	global_load_dwordx4 v[104:107], v[186:187], off offset:32
	global_load_dwordx4 v[108:111], v[188:189], off offset:32
	global_load_dwordx4 v[136:139], v[190:191], off offset:32
	global_load_dwordx4 v[140:143], v[194:195], off offset:32
	global_load_dwordx4 v[154:157], v[186:187], off offset:64
	global_load_dwordx4 v[158:161], v[188:189], off offset:64
	global_load_dwordx4 v[162:165], v[190:191], off offset:64
	global_load_dwordx4 v[166:169], v[194:195], off offset:64
	global_load_dwordx4 v[170:173], v[186:187], off offset:96
	global_load_dwordx4 v[174:177], v[188:189], off offset:96
	global_load_dwordx4 v[178:181], v[190:191], off offset:96
	global_load_dwordx4 v[182:185], v[194:195], off offset:96
	ds_read_b128 v[72:75], v70
	ds_read_b128 v[76:79], v70 offset:1024
	s_waitcnt vmcnt(15) lgkmcnt(1)
	v_mfma_f32_32x32x16_bf16 v[0:15], v[88:91], v[72:75], v[0:15]
	global_load_dwordx4 v[88:91], v[186:187], off offset:128
	s_waitcnt vmcnt(15)
	v_mfma_f32_32x32x16_bf16 v[16:31], v[92:95], v[72:75], v[16:31]
	global_load_dwordx4 v[92:95], v[188:189], off offset:128
	s_waitcnt vmcnt(15)
	v_mfma_f32_32x32x16_bf16 v[32:47], v[96:99], v[72:75], v[32:47]
	global_load_dwordx4 v[96:99], v[190:191], off offset:128
	s_waitcnt vmcnt(15)
	v_mfma_f32_32x32x16_bf16 v[48:63], v[100:103], v[72:75], v[48:63]
	global_load_dwordx4 v[100:103], v[194:195], off offset:128
	ds_read_b128 v[72:75], v70 offset:2048
	s_waitcnt vmcnt(15) lgkmcnt(1)
	v_mfma_f32_32x32x16_bf16 v[0:15], v[104:107], v[76:79], v[0:15]
	global_load_dwordx4 v[104:107], v[186:187], off offset:160
	s_waitcnt vmcnt(15)
	v_mfma_f32_32x32x16_bf16 v[16:31], v[108:111], v[76:79], v[16:31]
	global_load_dwordx4 v[108:111], v[188:189], off offset:160
	s_waitcnt vmcnt(15)
	v_mfma_f32_32x32x16_bf16 v[32:47], v[136:139], v[76:79], v[32:47]
	global_load_dwordx4 v[136:139], v[190:191], off offset:160
	s_waitcnt vmcnt(15)
	v_mfma_f32_32x32x16_bf16 v[48:63], v[140:143], v[76:79], v[48:63]
	global_load_dwordx4 v[140:143], v[194:195], off offset:160
	ds_read_b128 v[76:79], v70 offset:3072
	s_waitcnt vmcnt(15) lgkmcnt(1)
	v_mfma_f32_32x32x16_bf16 v[0:15], v[154:157], v[72:75], v[0:15]
	global_load_dwordx4 v[154:157], v[186:187], off offset:192
	s_waitcnt vmcnt(15)
	v_mfma_f32_32x32x16_bf16 v[16:31], v[158:161], v[72:75], v[16:31]
	global_load_dwordx4 v[158:161], v[188:189], off offset:192
	s_waitcnt vmcnt(15)
	v_mfma_f32_32x32x16_bf16 v[32:47], v[162:165], v[72:75], v[32:47]
	global_load_dwordx4 v[162:165], v[190:191], off offset:192
	s_waitcnt vmcnt(15)
	v_mfma_f32_32x32x16_bf16 v[48:63], v[166:169], v[72:75], v[48:63]
	global_load_dwordx4 v[166:169], v[194:195], off offset:192
	ds_read_b128 v[72:75], v70 offset:4096
	s_waitcnt vmcnt(15) lgkmcnt(1)
	v_mfma_f32_32x32x16_bf16 v[0:15], v[170:173], v[76:79], v[0:15]
	global_load_dwordx4 v[170:173], v[186:187], off offset:224
	s_waitcnt vmcnt(15)
	v_mfma_f32_32x32x16_bf16 v[16:31], v[174:177], v[76:79], v[16:31]
	global_load_dwordx4 v[174:177], v[188:189], off offset:224
	s_waitcnt vmcnt(15)
	v_mfma_f32_32x32x16_bf16 v[32:47], v[178:181], v[76:79], v[32:47]
	global_load_dwordx4 v[178:181], v[190:191], off offset:224
	s_waitcnt vmcnt(15)
	v_mfma_f32_32x32x16_bf16 v[48:63], v[182:185], v[76:79], v[48:63]
	global_load_dwordx4 v[182:185], v[194:195], off offset:224
	ds_read_b128 v[76:79], v70 offset:5120
	s_waitcnt vmcnt(15) lgkmcnt(1)
	v_mfma_f32_32x32x16_bf16 v[0:15], v[88:91], v[72:75], v[0:15]
	s_waitcnt vmcnt(14)
	v_mfma_f32_32x32x16_bf16 v[16:31], v[92:95], v[72:75], v[16:31]
	s_waitcnt vmcnt(13)
	v_mfma_f32_32x32x16_bf16 v[32:47], v[96:99], v[72:75], v[32:47]
	s_waitcnt vmcnt(12)
	v_mfma_f32_32x32x16_bf16 v[48:63], v[100:103], v[72:75], v[48:63]
	ds_read_b128 v[72:75], v70 offset:6144
	s_waitcnt vmcnt(11) lgkmcnt(1)
	v_mfma_f32_32x32x16_bf16 v[0:15], v[104:107], v[76:79], v[0:15]
	s_waitcnt vmcnt(10)
; #define LAS __attribute__((address_space(3)))
; #define MFMA32(a, b, c) __builtin_amdgcn_mfma_f32_32x32x16_bf16((a), (b), (c), 0, 0, 0)
;     __device__ __forceinline__ bf16* U() const { return (bf16*)(ws + WS_U); }
; template <bool SAMPLE>
; __device__ __forceinline__ void mout_task(Ctx& C, int l, int unit, int h, int tb, const LAS float* cwl, const LAS float* gainl, LAS float* gsbuf, LAS s16x8* qfl, const bool st) {
;     ...
;             for (int vb = 0; vb < 4; ++vb) acc[vb] = MFMA32(*(const s16x8*)(cp + (size_t)vb * 4096 + 16 * ks), qv, acc[vb]); }
;     }
; #pragma unroll
;     for (int vb = 0; vb < 4; ++vb)
; #pragma unroll
;         for (int i = 0; i < 16; ++i) acc[vb][i] *= winter;
;     float den = 0.f;
;     const int nsb = SAMPLE ? 1 : tb + 1;
; #pragma unroll 1
;     for (int sb = 0; sb < nsb; ++sb) {
;         f32x16 S;
; #pragma unroll
;         for (int i = 0; i < 16; ++i) S[i] = 0.f;
;         const int sl = 32 * sb + r;
;         { s16x8 tk[8];
;           const bf16* kp = C.U() + (grow0 + sl) * UW + C_KM + h * 128 + 8 * hi;
; #pragma unroll
;           for (int ks = 0; ks < 8; ++ks) tk[ks] = *(const s16x8*)(kp + 16 * ks);
; #pragma unroll
;           for (int ks = 0; ks < 8; ++ks) S = MFMA32(tk[ks], qfl[ks * 64 + lane], S); }
;         const float e0 = (bt - mt) * LOG2E;
; #pragma unroll
;         for (int i4 = 0; i4 < 4; ++i4) { const f32x4 gs = *(const LAS f32x4*)(gsbuf + 32 * sb + 8 * i4 + 4 * hi);
; #pragma unroll
;             for (int e = 0; e < 4; ++e) { const int sidx = 32 * sb + 8 * i4 + 4 * hi + e;
	v_mfma_f32_32x32x16_bf16 v[16:31], v[108:111], v[76:79], v[16:31]
	s_waitcnt vmcnt(9)
	v_mfma_f32_32x32x16_bf16 v[32:47], v[136:139], v[76:79], v[32:47]
	s_waitcnt vmcnt(8)
	v_mfma_f32_32x32x16_bf16 v[48:63], v[140:143], v[76:79], v[48:63]
	ds_read_b128 v[76:79], v70 offset:7168
	s_waitcnt vmcnt(7) lgkmcnt(1)
	v_mfma_f32_32x32x16_bf16 v[0:15], v[154:157], v[72:75], v[0:15]
	s_waitcnt vmcnt(6)
	v_mfma_f32_32x32x16_bf16 v[16:31], v[158:161], v[72:75], v[16:31]
	s_waitcnt vmcnt(5)
	v_mfma_f32_32x32x16_bf16 v[32:47], v[162:165], v[72:75], v[32:47]
	s_waitcnt vmcnt(4)
	v_mfma_f32_32x32x16_bf16 v[48:63], v[166:169], v[72:75], v[48:63]
	s_waitcnt vmcnt(3) lgkmcnt(0)
	v_mfma_f32_32x32x16_bf16 v[0:15], v[170:173], v[76:79], v[0:15]
	s_waitcnt vmcnt(2)
	v_mfma_f32_32x32x16_bf16 v[16:31], v[174:177], v[76:79], v[16:31]
	s_waitcnt vmcnt(1)
	v_mfma_f32_32x32x16_bf16 v[32:47], v[178:181], v[76:79], v[32:47]
	s_waitcnt vmcnt(0)
	v_mfma_f32_32x32x16_bf16 v[48:63], v[182:185], v[76:79], v[48:63]
	ds_read_b128 v[80:83], v127 offset:32768
	ds_read_b128 v[84:87], v127 offset:33792
	ds_read_b128 v[88:91], v127 offset:34816
	ds_read_b128 v[92:95], v127 offset:35840
	ds_read_b128 v[96:99], v127 offset:36864
	ds_read_b128 v[100:103], v127 offset:37888
	ds_read_b128 v[104:107], v127 offset:38912
	ds_read_b128 v[108:111], v127 offset:39936
	v_add_f32_e32 v66, v68, v69
	v_sub_f32_e32 v66, v66, v153
	s_add_i32 s40, s40, 1
	s_add_i32 s37, s22, 0x200
	s_lshl_b64 s[72:73], s[72:73], 14
	s_lshl_b64 s[74:75], s[74:75], 7
	v_mul_f32_e32 v66, 0x3fb8aa3b, v66
	s_add_u32 s72, s74, s72
	v_exp_f32_e32 v124, v66
	v_sub_f32_e32 v66, v69, v153
	s_addc_u32 s73, s75, s73
	v_mul_f32_e32 v154, 0x3fb8aa3b, v66
	v_lshlrev_b32_e32 v129, 2, v65
	v_add_u32_e32 v65, s37, v192
	v_mov_b64_e32 v[66:67], s[72:73]
	s_mov_b32 s81, 0x10800
	v_mad_i64_i32 v[136:137], s[72:73], v65, s81, v[66:67]
	v_lshl_add_u64 v[66:67], s[20:21], 0, v[192:193]
	v_mad_u64_u32 v[68:69], s[72:73], v66, s61, 0
	v_mad_i32_i24 v65, v67, s61, v69
	v_or_b32_e32 v64, v68, v64
	v_pk_mul_f32 v[14:15], v[124:125], v[14:15] op_sel_hi:[0,1]
	v_pk_mul_f32 v[12:13], v[124:125], v[12:13] op_sel_hi:[0,1]
	v_pk_mul_f32 v[10:11], v[124:125], v[10:11] op_sel_hi:[0,1]
	v_pk_mul_f32 v[8:9], v[124:125], v[8:9] op_sel_hi:[0,1]
	v_pk_mul_f32 v[6:7], v[124:125], v[6:7] op_sel_hi:[0,1]
	v_pk_mul_f32 v[4:5], v[124:125], v[4:5] op_sel_hi:[0,1]
	v_pk_mul_f32 v[2:3], v[124:125], v[2:3] op_sel_hi:[0,1]
	v_pk_mul_f32 v[0:1], v[124:125], v[0:1] op_sel_hi:[0,1]
	v_pk_mul_f32 v[30:31], v[124:125], v[30:31] op_sel_hi:[0,1]
	v_pk_mul_f32 v[28:29], v[124:125], v[28:29] op_sel_hi:[0,1]
	v_pk_mul_f32 v[26:27], v[124:125], v[26:27] op_sel_hi:[0,1]
	v_pk_mul_f32 v[24:25], v[124:125], v[24:25] op_sel_hi:[0,1]
	v_pk_mul_f32 v[22:23], v[124:125], v[22:23] op_sel_hi:[0,1]
	v_pk_mul_f32 v[20:21], v[124:125], v[20:21] op_sel_hi:[0,1]
	v_pk_mul_f32 v[18:19], v[124:125], v[18:19] op_sel_hi:[0,1]
	v_pk_mul_f32 v[16:17], v[124:125], v[16:17] op_sel_hi:[0,1]
	v_pk_mul_f32 v[46:47], v[124:125], v[46:47] op_sel_hi:[0,1]
	v_pk_mul_f32 v[44:45], v[124:125], v[44:45] op_sel_hi:[0,1]
	v_pk_mul_f32 v[42:43], v[124:125], v[42:43] op_sel_hi:[0,1]
	v_pk_mul_f32 v[40:41], v[124:125], v[40:41] op_sel_hi:[0,1]
	v_pk_mul_f32 v[38:39], v[124:125], v[38:39] op_sel_hi:[0,1]
	v_pk_mul_f32 v[36:37], v[124:125], v[36:37] op_sel_hi:[0,1]
	v_pk_mul_f32 v[34:35], v[124:125], v[34:35] op_sel_hi:[0,1]
	v_pk_mul_f32 v[32:33], v[124:125], v[32:33] op_sel_hi:[0,1]
	v_pk_mul_f32 v[62:63], v[124:125], v[62:63] op_sel_hi:[0,1]
	v_pk_mul_f32 v[60:61], v[124:125], v[60:61] op_sel_hi:[0,1]
	v_pk_mul_f32 v[58:59], v[124:125], v[58:59] op_sel_hi:[0,1]
	v_pk_mul_f32 v[56:57], v[124:125], v[56:57] op_sel_hi:[0,1]
	v_pk_mul_f32 v[54:55], v[124:125], v[54:55] op_sel_hi:[0,1]
	v_pk_mul_f32 v[52:53], v[124:125], v[52:53] op_sel_hi:[0,1]
	v_pk_mul_f32 v[50:51], v[124:125], v[50:51] op_sel_hi:[0,1]
	v_pk_mul_f32 v[48:49], v[124:125], v[48:49] op_sel_hi:[0,1]
	v_add_u32_e32 v155, -8, v120
	v_mov_b32_e32 v113, v120
	v_add_u32_e32 v115, -10, v120
	v_add_u32_e32 v126, -9, v120
	v_add_u32_e32 v117, -16, v120
	v_add_u32_e32 v128, -11, v120
	v_subrev_u32_e32 v119, 18, v120
	v_subrev_u32_e32 v130, 17, v120
	v_subrev_u32_e32 v121, 24, v120
	v_subrev_u32_e32 v132, 19, v120
	v_subrev_u32_e32 v125, 26, v120
	v_subrev_u32_e32 v134, 25, v120
	v_subrev_u32_e32 v156, 27, v120
	v_add_u32_e32 v157, s77, v114
	v_or_b32_e32 v136, v136, v116
	v_lshl_add_u64 v[138:139], s[22:23], 1, v[64:65]
	v_mov_b32_e32 v123, 0
	v_mov_b32_e32 v158, v129

; __device__ __forceinline__ bf16 f2bf(float f) { return (bf16)(pk2(f, 0.f) & 0xffffu); }
; __device__ __forceinline__ float sigmoidf_(float x) { return __builtin_amdgcn_rcpf(1.f + fexp(-x)); }
;     __device__ __forceinline__ bf16* U() const { return (bf16*)(ws + WS_U); }
;     __device__ __forceinline__ f32x2_t pre(int rr, int cc) const { const bf16* p = U + (size_t)rr * UW + cc; f32x2_t o; o.x = bf1(p[cgate]); o.y = cadd >= 0 ? bf1(p[cadd]) : 0.f; return o; }
;     __device__ __forceinline__ void fin(int rr, int cc, float v, f32x2_t p) const { if (st) X[(size_t)rr * DM + cc] = p.x + p.y * v; }
; template <class F>
; __device__ __forceinline__ void mini_gemm(Ctx& C, const bf16* A, int lda, const bf16* Bt, int K, LAS unsigned char* lds, const F& epi) {
;     ...
;         if (kh == 0) {
;             f32x2_t pre[16];
; #pragma unroll
;             for (int i = 0; i < 16; ++i) pre[i] = epi.pre(row0 + 8 * (i >> 2) + 4 * hi + (i & 3), col0 + r);
; #pragma unroll
;             for (int i = 0; i < 16; ++i) { const float v = acc[i] + red[i * 64 + lane];
;                 epi.fin(row0 + 8 * (i >> 2) + 4 * hi + (i & 3), col0 + r, v, pre[i]); }
;     __device__ __forceinline__ void fin(int rr, int cc, float v, f32x2_t p) const { if (st) U[(size_t)rr * UW + cgate + cc] = f2bf(p.y + sigmoidf_(p.x) * v); }
.LBB0_1006:
	s_andn2_b64 vcc, exec, s[6:7]
	s_waitcnt lgkmcnt(0)
	s_barrier
	s_cbranch_vccnz .LBB0_1003
	v_lshlrev_b32_e32 v192, 1, v20
	v_or_b32_e32 v48, s13, v24
	v_lshl_add_u64 v[20:21], s[90:91], 0, v[192:193]
	v_mad_i64_i32 v[26:27], s[14:15], v48, s61, v[20:21]
	v_add_co_u32_e32 v26, vcc, 0x1000, v26
	v_or_b32_e32 v50, 1, v48
	s_nop 0
	v_addc_co_u32_e32 v27, vcc, 0, v27, vcc
	global_load_ushort v126, v[26:27], off offset:1024
	v_or_b32_e32 v52, 2, v48
	v_or_b32_e32 v54, 3, v48
	v_or_b32_e32 v56, 8, v48
	v_or_b32_e32 v58, 9, v48
	v_or_b32_e32 v43, 10, v48
	v_or_b32_e32 v41, 11, v48
	v_or_b32_e32 v39, 16, v48
	v_or_b32_e32 v36, 17, v48
	v_or_b32_e32 v34, 18, v48
	v_or_b32_e32 v35, 19, v48
	v_or_b32_e32 v30, 24, v48
	v_or_b32_e32 v31, 25, v48
	v_mad_i64_i32 v[26:27], s[14:15], v50, s61, v[20:21]
	v_add_co_u32_e32 v26, vcc, 0x1000, v26
	s_nop 1
	v_addc_co_u32_e32 v27, vcc, 0, v27, vcc
	global_load_ushort v127, v[26:27], off offset:1024
	v_mad_i64_i32 v[26:27], s[14:15], v52, s61, v[20:21]
	v_add_co_u32_e32 v26, vcc, 0x1000, v26
	s_nop 1
	v_addc_co_u32_e32 v27, vcc, 0, v27, vcc
	global_load_ushort v128, v[26:27], off offset:1024
	v_mad_i64_i32 v[26:27], s[14:15], v54, s61, v[20:21]
	v_add_co_u32_e32 v26, vcc, 0x1000, v26
	s_nop 1
	v_addc_co_u32_e32 v27, vcc, 0, v27, vcc
	global_load_ushort v129, v[26:27], off offset:1024
	v_mad_i64_i32 v[26:27], s[14:15], v56, s61, v[20:21]
	v_add_co_u32_e32 v26, vcc, 0x1000, v26
	s_nop 1
	v_addc_co_u32_e32 v27, vcc, 0, v27, vcc
	global_load_ushort v130, v[26:27], off offset:1024
	v_mad_i64_i32 v[26:27], s[14:15], v58, s61, v[20:21]
	v_add_co_u32_e32 v26, vcc, 0x1000, v26
	s_nop 1
	v_addc_co_u32_e32 v27, vcc, 0, v27, vcc
	global_load_ushort v131, v[26:27], off offset:1024
	v_mad_i64_i32 v[26:27], s[14:15], v43, s61, v[20:21]
	v_add_co_u32_e32 v26, vcc, 0x1000, v26
	s_nop 1
	v_addc_co_u32_e32 v27, vcc, 0, v27, vcc
	global_load_ushort v132, v[26:27], off offset:1024
	v_mad_i64_i32 v[26:27], s[14:15], v41, s61, v[20:21]
	v_add_co_u32_e32 v26, vcc, 0x1000, v26
	s_nop 1
	v_addc_co_u32_e32 v27, vcc, 0, v27, vcc
	global_load_ushort v133, v[26:27], off offset:1024
	v_mad_i64_i32 v[26:27], s[14:15], v39, s61, v[20:21]
	v_add_co_u32_e32 v26, vcc, 0x1000, v26
	s_nop 1
	v_addc_co_u32_e32 v27, vcc, 0, v27, vcc
	global_load_ushort v134, v[26:27], off offset:1024
	v_mad_i64_i32 v[26:27], s[14:15], v36, s61, v[20:21]
	v_add_co_u32_e32 v26, vcc, 0x1000, v26
	s_nop 1
	v_addc_co_u32_e32 v27, vcc, 0, v27, vcc
	global_load_ushort v135, v[26:27], off offset:1024
	v_mad_i64_i32 v[26:27], s[14:15], v34, s61, v[20:21]
	v_add_co_u32_e32 v26, vcc, 0x1000, v26
	s_nop 1
	v_addc_co_u32_e32 v27, vcc, 0, v27, vcc
	global_load_ushort v136, v[26:27], off offset:1024
	v_mad_i64_i32 v[26:27], s[14:15], v35, s61, v[20:21]
	v_add_co_u32_e32 v26, vcc, 0x1000, v26
	s_nop 1
	v_addc_co_u32_e32 v27, vcc, 0, v27, vcc
	global_load_ushort v137, v[26:27], off offset:1024
	v_mad_i64_i32 v[26:27], s[14:15], v30, s61, v[20:21]
	v_add_co_u32_e32 v26, vcc, 0x1000, v26
	s_nop 1
	v_addc_co_u32_e32 v27, vcc, 0, v27, vcc
	global_load_ushort v138, v[26:27], off offset:1024
	v_mad_i64_i32 v[26:27], s[14:15], v31, s61, v[20:21]
	v_add_co_u32_e32 v26, vcc, 0x1000, v26
	s_nop 1
	v_addc_co_u32_e32 v27, vcc, 0, v27, vcc
	global_load_ushort v139, v[26:27], off offset:1024
	v_or_b32_e32 v27, 26, v48
	v_mad_i64_i32 v[28:29], s[14:15], v27, s61, v[20:21]
	v_add_co_u32_e32 v28, vcc, 0x1000, v28
	v_addc_co_u32_e32 v29, vcc, 0, v29, vcc
	global_load_ushort v140, v[28:29], off offset:1024
	v_or_b32_e32 v26, 27, v48
	v_mad_i64_i32 v[46:47], s[14:15], v26, s61, v[20:21]
	v_add_co_u32_e32 v46, vcc, 0x1000, v46
	v_lshl_add_u64 v[20:21], s[82:83], 0, v[192:193]
	s_nop 0
	v_addc_co_u32_e32 v47, vcc, 0, v47, vcc
	global_load_ushort v28, v[46:47], off offset:1024
	s_waitcnt vmcnt(0)
	v_lshlrev_b32_e32 v49, 16, v126
	v_lshlrev_b32_e32 v51, 16, v127
	v_lshlrev_b32_e32 v53, 16, v128
	v_lshlrev_b32_e32 v55, 16, v129
	v_lshlrev_b32_e32 v57, 16, v130
	v_lshlrev_b32_e32 v59, 16, v131
	v_lshlrev_b32_e32 v44, 16, v132
	v_lshlrev_b32_e32 v45, 16, v133
	v_lshlrev_b32_e32 v42, 16, v134
	v_lshlrev_b32_e32 v40, 16, v135
	v_lshlrev_b32_e32 v37, 16, v136
	v_lshlrev_b32_e32 v38, 16, v137
	v_lshlrev_b32_e32 v32, 16, v138
	v_lshlrev_b32_e32 v33, 16, v139
	v_lshlrev_b32_e32 v29, 16, v140
	ds_read2st64_b32 v[46:47], v23 offset1:1
	s_waitcnt lgkmcnt(0)
	v_add_f32_e32 v0, v0, v46
	v_mul_f32_e32 v46, 0xbfb8aa3b, v49
	v_exp_f32_e32 v46, v46
	v_mad_i64_i32 v[48:49], s[14:15], v48, s61, v[20:21]
	v_add_f32_e32 v46, 1.0, v46
	v_rcp_f32_e32 v46, v46
	s_waitcnt vmcnt(0)
; __device__ __forceinline__ bf16 f2bf(float f) { return (bf16)(pk2(f, 0.f) & 0xffffu); }
; __device__ __forceinline__ float sigmoidf_(float x) { return __builtin_amdgcn_rcpf(1.f + fexp(-x)); }
;     __device__ __forceinline__ bf16* U() const { return (bf16*)(ws + WS_U); }
;     __device__ __forceinline__ f32x2_t pre(int rr, int cc) const { const bf16* p = U + (size_t)rr * UW + cc; f32x2_t o; o.x = bf1(p[cgate]); o.y = cadd >= 0 ? bf1(p[cadd]) : 0.f; return o; }
;     __device__ __forceinline__ void fin(int rr, int cc, float v, f32x2_t p) const { if (st) X[(size_t)rr * DM + cc] = p.x + p.y * v; }
; #define PHASE_BEGIN() do { int t_ = C.tid; asm volatile("" : "+v"(t_)); C.tid = t_; C.lane = t_ & 63; C.wave = __builtin_amdgcn_readfirstlane(t_ >> 6); \
;         int g_ = C.G, b_ = C.bid; asm volatile("" : "+s"(g_), "+s"(b_)); C.G = g_; C.bid = b_; } while (0)
; template <class F>
; __device__ __forceinline__ void mini_gemm(Ctx& C, const bf16* A, int lda, const bf16* Bt, int K, LAS unsigned char* lds, const F& epi) {
;     ...
;             for (int i = 0; i < 16; ++i) pre[i] = epi.pre(row0 + 8 * (i >> 2) + 4 * hi + (i & 3), col0 + r);
; #pragma unroll
;             for (int i = 0; i < 16; ++i) { const float v = acc[i] + red[i * 64 + lane];
;                 epi.fin(row0 + 8 * (i >> 2) + 4 * hi + (i & 3), col0 + r, v, pre[i]); }
;         }
;         __syncthreads();
;     }
; }
;     __device__ __forceinline__ void fin(int rr, int cc, float v, f32x2_t p) const { if (st) U[(size_t)rr * UW + cgate + cc] = f2bf(p.y + sigmoidf_(p.x) * v); }
; __global__ void __launch_bounds__(512) fwd_megakernel(Args args) {
;     ...
;             __threadfence(); __syncthreads(); PHASE_BEGIN();
	v_lshlrev_b32_e32 v28, 16, v28
	v_fma_f32 v0, v46, v0, 0
	v_cvt_pk_bf16_f32 v0, v0, s0
	global_store_short v[48:49], v0, off
	v_add_f32_e32 v0, v1, v47
	v_mul_f32_e32 v1, 0xbfb8aa3b, v51
	v_exp_f32_e32 v1, v1
	s_nop 0
	v_add_f32_e32 v1, 1.0, v1
	v_rcp_f32_e32 v1, v1
	s_nop 0
	v_fma_f32 v0, v1, v0, 0
	v_cvt_pk_bf16_f32 v46, v0, s0
	v_mad_i64_i32 v[0:1], s[14:15], v50, s61, v[20:21]
	global_store_short v[0:1], v46, off
	ds_read2st64_b32 v[0:1], v23 offset0:2 offset1:3
	v_mad_i64_i32 v[46:47], s[14:15], v52, s61, v[20:21]
	s_waitcnt lgkmcnt(0)
	v_add_f32_e32 v0, v2, v0
	v_mul_f32_e32 v2, 0xbfb8aa3b, v53
	v_exp_f32_e32 v2, v2
	s_nop 0
	v_add_f32_e32 v2, 1.0, v2
	v_rcp_f32_e32 v2, v2
	s_nop 0
	v_fma_f32 v0, v2, v0, 0
	v_cvt_pk_bf16_f32 v0, v0, s0
	global_store_short v[46:47], v0, off
	v_add_f32_e32 v0, v3, v1
	v_mul_f32_e32 v1, 0xbfb8aa3b, v55
	v_exp_f32_e32 v1, v1
	s_nop 0
	v_add_f32_e32 v1, 1.0, v1
	v_rcp_f32_e32 v1, v1
	s_nop 0
	v_fma_f32 v0, v1, v0, 0
	v_cvt_pk_bf16_f32 v2, v0, s0
	v_mad_i64_i32 v[0:1], s[14:15], v54, s61, v[20:21]
	global_store_short v[0:1], v2, off
	v_mul_f32_e32 v2, 0xbfb8aa3b, v57
	v_exp_f32_e32 v2, v2
	ds_read2st64_b32 v[0:1], v23 offset0:4 offset1:5
	v_add_f32_e32 v2, 1.0, v2
	v_rcp_f32_e32 v2, v2
	s_waitcnt lgkmcnt(0)
	v_add_f32_e32 v0, v4, v0
	v_fma_f32 v0, v2, v0, 0
	v_cvt_pk_bf16_f32 v0, v0, s0
	v_mad_i64_i32 v[2:3], s[14:15], v56, s61, v[20:21]
	global_store_short v[2:3], v0, off
	v_add_f32_e32 v0, v5, v1
	v_mul_f32_e32 v1, 0xbfb8aa3b, v59
	v_exp_f32_e32 v1, v1
	s_nop 0
	v_add_f32_e32 v1, 1.0, v1
	v_rcp_f32_e32 v1, v1
	s_nop 0
	v_fma_f32 v0, v1, v0, 0
	v_cvt_pk_bf16_f32 v2, v0, s0
	v_mad_i64_i32 v[0:1], s[14:15], v58, s61, v[20:21]
	global_store_short v[0:1], v2, off
	v_mul_f32_e32 v2, 0xbfb8aa3b, v44
	v_exp_f32_e32 v2, v2
	ds_read2st64_b32 v[0:1], v23 offset0:6 offset1:7
	v_add_f32_e32 v2, 1.0, v2
	v_rcp_f32_e32 v2, v2
	s_waitcnt lgkmcnt(0)
	v_add_f32_e32 v0, v6, v0
	v_fma_f32 v0, v2, v0, 0
	v_cvt_pk_bf16_f32 v0, v0, s0
	v_mad_i64_i32 v[2:3], s[14:15], v43, s61, v[20:21]
	global_store_short v[2:3], v0, off
	v_add_f32_e32 v0, v7, v1
	v_mul_f32_e32 v1, 0xbfb8aa3b, v45
	v_exp_f32_e32 v1, v1
	s_nop 0
	v_add_f32_e32 v1, 1.0, v1
	v_rcp_f32_e32 v1, v1
	s_nop 0
	v_fma_f32 v0, v1, v0, 0
	v_cvt_pk_bf16_f32 v2, v0, s0
	v_mad_i64_i32 v[0:1], s[14:15], v41, s61, v[20:21]
	global_store_short v[0:1], v2, off
	v_mul_f32_e32 v2, 0xbfb8aa3b, v42
	v_exp_f32_e32 v2, v2
	ds_read2st64_b32 v[0:1], v23 offset0:8 offset1:9
	v_add_f32_e32 v2, 1.0, v2
	v_rcp_f32_e32 v2, v2
	s_waitcnt lgkmcnt(0)
	v_add_f32_e32 v0, v8, v0
	v_fma_f32 v0, v2, v0, 0
	v_cvt_pk_bf16_f32 v0, v0, s0
	v_mad_i64_i32 v[2:3], s[14:15], v39, s61, v[20:21]
	global_store_short v[2:3], v0, off
	v_add_f32_e32 v0, v9, v1
	v_mul_f32_e32 v1, 0xbfb8aa3b, v40
	v_exp_f32_e32 v1, v1
	s_nop 0
	v_add_f32_e32 v1, 1.0, v1
	v_rcp_f32_e32 v1, v1
	s_nop 0
	v_fma_f32 v0, v1, v0, 0
	v_cvt_pk_bf16_f32 v2, v0, s0
	v_mad_i64_i32 v[0:1], s[14:15], v36, s61, v[20:21]
	global_store_short v[0:1], v2, off
	v_mul_f32_e32 v2, 0xbfb8aa3b, v37
	v_exp_f32_e32 v2, v2
	ds_read2st64_b32 v[0:1], v23 offset0:10 offset1:11
	v_add_f32_e32 v2, 1.0, v2
	v_rcp_f32_e32 v2, v2
	s_waitcnt lgkmcnt(0)
	v_add_f32_e32 v0, v10, v0
	v_fma_f32 v0, v2, v0, 0
	v_cvt_pk_bf16_f32 v0, v0, s0
	v_mad_i64_i32 v[2:3], s[14:15], v34, s61, v[20:21]
	global_store_short v[2:3], v0, off
	v_add_f32_e32 v0, v11, v1
	v_mul_f32_e32 v1, 0xbfb8aa3b, v38
	v_exp_f32_e32 v1, v1
	s_nop 0
	v_add_f32_e32 v1, 1.0, v1
	v_rcp_f32_e32 v1, v1
	s_nop 0
	v_fma_f32 v0, v1, v0, 0
	v_cvt_pk_bf16_f32 v2, v0, s0
	v_mad_i64_i32 v[0:1], s[14:15], v35, s61, v[20:21]
	global_store_short v[0:1], v2, off
	v_mul_f32_e32 v2, 0xbfb8aa3b, v32
	v_exp_f32_e32 v2, v2
	ds_read2st64_b32 v[0:1], v23 offset0:12 offset1:13
	v_add_f32_e32 v2, 1.0, v2
	v_rcp_f32_e32 v2, v2
	s_waitcnt lgkmcnt(0)
	v_add_f32_e32 v0, v12, v0
	v_fma_f32 v0, v2, v0, 0
	v_cvt_pk_bf16_f32 v0, v0, s0
	v_mad_i64_i32 v[2:3], s[14:15], v30, s61, v[20:21]
	global_store_short v[2:3], v0, off
	v_add_f32_e32 v0, v13, v1
	v_mul_f32_e32 v1, 0xbfb8aa3b, v33
	v_exp_f32_e32 v1, v1
	s_nop 0
	v_add_f32_e32 v1, 1.0, v1
	v_rcp_f32_e32 v1, v1
	s_nop 0
	v_fma_f32 v0, v1, v0, 0
	v_cvt_pk_bf16_f32 v2, v0, s0
	v_mad_i64_i32 v[0:1], s[14:15], v31, s61, v[20:21]
	global_store_short v[0:1], v2, off
	v_mul_f32_e32 v2, 0xbfb8aa3b, v29
	v_exp_f32_e32 v2, v2
	ds_read2st64_b32 v[0:1], v23 offset0:14 offset1:15
	v_add_f32_e32 v2, 1.0, v2
	v_rcp_f32_e32 v2, v2
	s_waitcnt lgkmcnt(0)
	v_add_f32_e32 v0, v14, v0
	v_fma_f32 v0, v2, v0, 0
	v_cvt_pk_bf16_f32 v0, v0, s0
	v_mad_i64_i32 v[2:3], s[14:15], v27, s61, v[20:21]
	global_store_short v[2:3], v0, off
	v_add_f32_e32 v0, v15, v1
	v_mul_f32_e32 v1, 0xbfb8aa3b, v28
	v_exp_f32_e32 v1, v1
	s_nop 0
	v_add_f32_e32 v1, 1.0, v1
	v_rcp_f32_e32 v1, v1
	s_nop 0
	v_fma_f32 v0, v1, v0, 0
	v_cvt_pk_bf16_f32 v2, v0, s0
	v_mad_i64_i32 v[0:1], s[14:15], v26, s61, v[20:21]
	global_store_short v[0:1], v2, off
	s_branch .LBB0_1003
.LBB0_1008:
	s_waitcnt vmcnt(0)

;     __device__ __forceinline__ bf16* U() const { return (bf16*)(ws + WS_U); }
; #define PHASE_BEGIN() do { int t_ = C.tid; asm volatile("" : "+v"(t_)); C.tid = t_; C.lane = t_ & 63; C.wave = __builtin_amdgcn_readfirstlane(t_ >> 6); \
;         int g_ = C.G, b_ = C.bid; asm volatile("" : "+s"(g_), "+s"(b_)); C.G = g_; C.bid = b_; } while (0)
;     __device__ __forceinline__ bool next(int i, Unit& u) const {
;         const long L = (long)i * G + c;
;         if (L < nwg0) { map((int)L, nwg0, nM0, nN0, u); u.kind = 0; return true; }
; __global__ void __launch_bounds__(512) fwd_megakernel(Args args) {
;     ...
;             __threadfence(); __syncthreads(); PHASE_BEGIN();
;             S.init(C.U() + C_OM, C.W() + W_BM, MP, 1024, nullptr, nullptr, 0, 0, UW, 512, C.G, C.bid);
;             pg8::EpiGate E2{C.U() + C_GM, C.U() + C_GA, C.U() + C_GM, st};
;             pg8::gemm_phase(lds, g, S, E2, C.tid);
	s_barrier
	s_cmpk_lt_i32 s2, 0x200
	v_readlane_b32 s40, v255, 50
	s_movk_i32 s58, 0x1200
	s_cselect_b64 s[4:5], -1, 0
	s_cmpk_gt_i32 s2, 0x1ff
	v_readfirstlane_b32 s43, v202
	v_readlane_b32 s41, v255, 51
	s_cbranch_scc1 .LBB0_1014
	s_ashr_i32 s3, s2, 31
	s_lshr_b32 s3, s3, 29
	s_add_i32 s3, s2, s3
	s_and_b32 s6, s3, -8
	s_sub_i32 s8, s2, s6
	s_cmp_gt_i32 s8, -1
	s_mov_b64 s[6:7], -1
	s_cbranch_scc0 .LBB0_1011
	s_lshl_b32 s9, s8, 6
	s_mov_b64 s[6:7], 0

; __device__ __forceinline__ bf16 f2bf(float f) { return (bf16)(pk2(f, 0.f) & 0xffffu); }
; __device__ __forceinline__ float sigmoidf_(float x) { return __builtin_amdgcn_rcpf(1.f + fexp(-x)); }
;     __device__ __forceinline__ bf16* U() const { return (bf16*)(ws + WS_U); }
;     __device__ __forceinline__ f32x2_t pre(int rr, int cc) const { const bf16* p = U + (size_t)rr * UW + cc; f32x2_t o; o.x = bf1(p[cgate]); o.y = cadd >= 0 ? bf1(p[cadd]) : 0.f; return o; }
;     __device__ __forceinline__ void fin(int rr, int cc, float v, f32x2_t p) const { if (st) X[(size_t)rr * DM + cc] = p.x + p.y * v; }
; template <class F>
; __device__ __forceinline__ void mini_gemm(Ctx& C, const bf16* A, int lda, const bf16* Bt, int K, LAS unsigned char* lds, const F& epi) {
;     ...
;         if (kh == 0) {
;             f32x2_t pre[16];
; #pragma unroll
;             for (int i = 0; i < 16; ++i) pre[i] = epi.pre(row0 + 8 * (i >> 2) + 4 * hi + (i & 3), col0 + r);
; #pragma unroll
;             for (int i = 0; i < 16; ++i) { const float v = acc[i] + red[i * 64 + lane];
;                 epi.fin(row0 + 8 * (i >> 2) + 4 * hi + (i & 3), col0 + r, v, pre[i]); }
;     __device__ __forceinline__ void fin(int rr, int cc, float v, f32x2_t p) const { if (st) U[(size_t)rr * UW + cgate + cc] = f2bf(p.y + sigmoidf_(p.x) * v); }
.LBB0_1073:
	s_andn2_b64 vcc, exec, s[6:7]
	s_waitcnt lgkmcnt(0)
	s_barrier
	s_cbranch_vccnz .LBB0_1070
	v_lshlrev_b32_e32 v192, 1, v20
	v_or_b32_e32 v61, s13, v24
	v_lshl_add_u64 v[20:21], s[90:91], 0, v[192:193]
	v_mad_i64_i32 v[26:27], s[14:15], v61, s61, v[20:21]
	v_add_co_u32_e32 v26, vcc, 0x1000, v26
	v_or_b32_e32 v62, 1, v61
	s_nop 0
	v_addc_co_u32_e32 v27, vcc, 0, v27, vcc
	global_load_ushort v126, v[26:27], off offset:1024
	v_or_b32_e32 v59, 2, v61
	global_load_ushort v127, v[26:27], off offset:3072
	v_or_b32_e32 v70, 3, v61
	v_or_b32_e32 v56, 8, v61
	v_or_b32_e32 v60, 9, v61
	v_or_b32_e32 v50, 10, v61
	v_or_b32_e32 v38, 11, v61
	v_or_b32_e32 v39, 16, v61
	v_or_b32_e32 v37, 17, v61
	v_or_b32_e32 v35, 18, v61
	v_or_b32_e32 v47, 19, v61
	v_or_b32_e32 v32, 24, v61
	v_or_b32_e32 v36, 25, v61
	v_mad_i64_i32 v[26:27], s[14:15], v62, s61, v[20:21]
	v_add_co_u32_e32 v26, vcc, 0x1000, v26
	s_nop 0
	v_addc_co_u32_e32 v27, vcc, 0, v27, vcc
	global_load_ushort v128, v[26:27], off offset:1024
	global_load_ushort v129, v[26:27], off offset:3072
	v_mad_i64_i32 v[26:27], s[14:15], v59, s61, v[20:21]
	v_add_co_u32_e32 v26, vcc, 0x1000, v26
	s_nop 1
	v_addc_co_u32_e32 v27, vcc, 0, v27, vcc
	global_load_ushort v130, v[26:27], off offset:1024
	global_load_ushort v131, v[26:27], off offset:3072
	v_mad_i64_i32 v[26:27], s[14:15], v70, s61, v[20:21]
	v_add_co_u32_e32 v26, vcc, 0x1000, v26
	s_nop 1
	v_addc_co_u32_e32 v27, vcc, 0, v27, vcc
	global_load_ushort v132, v[26:27], off offset:1024
	global_load_ushort v133, v[26:27], off offset:3072
	v_mad_i64_i32 v[26:27], s[14:15], v56, s61, v[20:21]
	v_add_co_u32_e32 v26, vcc, 0x1000, v26
	s_nop 1
	v_addc_co_u32_e32 v27, vcc, 0, v27, vcc
	global_load_ushort v134, v[26:27], off offset:1024
	global_load_ushort v135, v[26:27], off offset:3072
	v_mad_i64_i32 v[26:27], s[14:15], v60, s61, v[20:21]
	v_add_co_u32_e32 v26, vcc, 0x1000, v26
	s_nop 1
	v_addc_co_u32_e32 v27, vcc, 0, v27, vcc
	global_load_ushort v136, v[26:27], off offset:1024
	global_load_ushort v137, v[26:27], off offset:3072
	v_mad_i64_i32 v[26:27], s[14:15], v50, s61, v[20:21]
	v_add_co_u32_e32 v26, vcc, 0x1000, v26
	s_nop 1
	v_addc_co_u32_e32 v27, vcc, 0, v27, vcc
	global_load_ushort v138, v[26:27], off offset:1024
	global_load_ushort v139, v[26:27], off offset:3072
	v_mad_i64_i32 v[26:27], s[14:15], v38, s61, v[20:21]
	v_add_co_u32_e32 v26, vcc, 0x1000, v26
	s_nop 1
	v_addc_co_u32_e32 v27, vcc, 0, v27, vcc
	global_load_ushort v140, v[26:27], off offset:1024
	global_load_ushort v141, v[26:27], off offset:3072
	v_mad_i64_i32 v[26:27], s[14:15], v39, s61, v[20:21]
	v_add_co_u32_e32 v26, vcc, 0x1000, v26
	s_nop 1
	v_addc_co_u32_e32 v27, vcc, 0, v27, vcc
	global_load_ushort v142, v[26:27], off offset:1024
	global_load_ushort v143, v[26:27], off offset:3072
	v_mad_i64_i32 v[26:27], s[14:15], v37, s61, v[20:21]
	v_add_co_u32_e32 v26, vcc, 0x1000, v26
	s_nop 1
	v_addc_co_u32_e32 v27, vcc, 0, v27, vcc
	global_load_ushort v144, v[26:27], off offset:1024
	global_load_ushort v145, v[26:27], off offset:3072
	v_mad_i64_i32 v[26:27], s[14:15], v35, s61, v[20:21]
	v_add_co_u32_e32 v26, vcc, 0x1000, v26
	s_nop 1
	v_addc_co_u32_e32 v27, vcc, 0, v27, vcc
	global_load_ushort v146, v[26:27], off offset:1024
	global_load_ushort v147, v[26:27], off offset:3072
	v_mad_i64_i32 v[26:27], s[14:15], v47, s61, v[20:21]
	v_add_co_u32_e32 v26, vcc, 0x1000, v26
	s_nop 1
	v_addc_co_u32_e32 v27, vcc, 0, v27, vcc
	global_load_ushort v148, v[26:27], off offset:1024
	global_load_ushort v149, v[26:27], off offset:3072
	v_mad_i64_i32 v[26:27], s[14:15], v32, s61, v[20:21]
	v_add_co_u32_e32 v26, vcc, 0x1000, v26
	s_nop 1
	v_addc_co_u32_e32 v27, vcc, 0, v27, vcc
	global_load_ushort v150, v[26:27], off offset:1024
	global_load_ushort v151, v[26:27], off offset:3072
	v_mad_i64_i32 v[26:27], s[14:15], v36, s61, v[20:21]
	v_add_co_u32_e32 v26, vcc, 0x1000, v26
	s_nop 1
	v_addc_co_u32_e32 v27, vcc, 0, v27, vcc
	global_load_ushort v152, v[26:27], off offset:1024
	global_load_ushort v153, v[26:27], off offset:3072
	v_or_b32_e32 v28, 26, v61
	v_mad_i64_i32 v[26:27], s[14:15], v28, s61, v[20:21]
	v_add_co_u32_e32 v26, vcc, 0x1000, v26
	s_nop 1
	v_addc_co_u32_e32 v27, vcc, 0, v27, vcc
	global_load_ushort v154, v[26:27], off offset:1024
	global_load_ushort v26, v[26:27], off offset:3072
	s_waitcnt vmcnt(0)
	v_lshlrev_b32_e32 v66, 16, v126
	v_lshlrev_b32_e32 v71, 16, v127
	v_mul_f32_e32 v71, 0xbfb8aa3b, v71
	v_exp_f32_e32 v71, v71
	s_nop 0
	v_add_f32_e32 v71, 1.0, v71
	v_rcp_f32_e32 v71, v71
	v_lshlrev_b32_e32 v65, 16, v128
	v_lshlrev_b32_e32 v69, 16, v129
	v_lshlrev_b32_e32 v63, 16, v130
	v_lshlrev_b32_e32 v67, 16, v131
	v_lshlrev_b32_e32 v72, 16, v132
	v_lshlrev_b32_e32 v73, 16, v133
	v_lshlrev_b32_e32 v57, 16, v134
	v_lshlrev_b32_e32 v58, 16, v135
	v_lshlrev_b32_e32 v64, 16, v136
	v_lshlrev_b32_e32 v68, 16, v137
	v_lshlrev_b32_e32 v51, 16, v138
	v_lshlrev_b32_e32 v54, 16, v139
	v_lshlrev_b32_e32 v49, 16, v140
	v_lshlrev_b32_e32 v55, 16, v141
	v_lshlrev_b32_e32 v43, 16, v142
	v_lshlrev_b32_e32 v48, 16, v143
	v_lshlrev_b32_e32 v42, 16, v144
	v_lshlrev_b32_e32 v46, 16, v145
	v_lshlrev_b32_e32 v40, 16, v146
	v_lshlrev_b32_e32 v44, 16, v147
	v_lshlrev_b32_e32 v52, 16, v148
	v_lshlrev_b32_e32 v53, 16, v149
	v_lshlrev_b32_e32 v33, 16, v150
	v_lshlrev_b32_e32 v34, 16, v151
	v_lshlrev_b32_e32 v41, 16, v152
	v_lshlrev_b32_e32 v45, 16, v153
	v_lshlrev_b32_e32 v29, 16, v154
	s_waitcnt vmcnt(0)
; __device__ __forceinline__ bf16 f2bf(float f) { return (bf16)(pk2(f, 0.f) & 0xffffu); }
; __device__ __forceinline__ float sigmoidf_(float x) { return __builtin_amdgcn_rcpf(1.f + fexp(-x)); }
;     __device__ __forceinline__ bf16* U() const { return (bf16*)(ws + WS_U); }
;     __device__ __forceinline__ f32x2_t pre(int rr, int cc) const { const bf16* p = U + (size_t)rr * UW + cc; f32x2_t o; o.x = bf1(p[cgate]); o.y = cadd >= 0 ? bf1(p[cadd]) : 0.f; return o; }
;     __device__ __forceinline__ void fin(int rr, int cc, float v, f32x2_t p) const { if (st) X[(size_t)rr * DM + cc] = p.x + p.y * v; }
; template <class F>
; __device__ __forceinline__ void mini_gemm(Ctx& C, const bf16* A, int lda, const bf16* Bt, int K, LAS unsigned char* lds, const F& epi) {
;     ...
;         if (kh == 0) {
;             f32x2_t pre[16];
; #pragma unroll
;             for (int i = 0; i < 16; ++i) pre[i] = epi.pre(row0 + 8 * (i >> 2) + 4 * hi + (i & 3), col0 + r);
; #pragma unroll
;             for (int i = 0; i < 16; ++i) { const float v = acc[i] + red[i * 64 + lane];
;                 epi.fin(row0 + 8 * (i >> 2) + 4 * hi + (i & 3), col0 + r, v, pre[i]); }
;     __device__ __forceinline__ void fin(int rr, int cc, float v, f32x2_t p) const { if (st) U[(size_t)rr * UW + cgate + cc] = f2bf(p.y + sigmoidf_(p.x) * v); }
	v_lshlrev_b32_e32 v30, 16, v26
	v_or_b32_e32 v26, 27, v61
	v_mad_i64_i32 v[20:21], s[14:15], v26, s61, v[20:21]
	v_add_co_u32_e32 v74, vcc, 0x1000, v20
	s_nop 1
	v_addc_co_u32_e32 v75, vcc, 0, v21, vcc
	global_load_ushort v20, v[74:75], off offset:1024
	global_load_ushort v31, v[74:75], off offset:3072
	ds_read2st64_b32 v[74:75], v23 offset1:1
	s_waitcnt lgkmcnt(0)
	v_add_f32_e32 v0, v0, v74
	v_fmac_f32_e32 v66, v71, v0
	v_cvt_pk_bf16_f32 v0, v66, s0
	s_waitcnt vmcnt(1)
	v_lshlrev_b32_e32 v27, 16, v20
	v_lshl_add_u64 v[20:21], s[70:71], 0, v[192:193]
	v_mad_i64_i32 v[76:77], s[14:15], v61, s61, v[20:21]
	global_store_short v[76:77], v0, off
	v_add_f32_e32 v0, v1, v75
	v_mul_f32_e32 v1, 0xbfb8aa3b, v69
	v_exp_f32_e32 v1, v1
	s_waitcnt vmcnt(1)
	v_lshlrev_b32_e32 v31, 16, v31
	v_add_f32_e32 v1, 1.0, v1
	v_rcp_f32_e32 v1, v1
	s_nop 0
	v_fmac_f32_e32 v65, v1, v0
	v_cvt_pk_bf16_f32 v61, v65, s0
	v_mad_i64_i32 v[0:1], s[14:15], v62, s61, v[20:21]
	global_store_short v[0:1], v61, off
	ds_read2st64_b32 v[0:1], v23 offset0:2 offset1:3
	s_waitcnt lgkmcnt(0)
	v_add_f32_e32 v0, v2, v0
	v_mul_f32_e32 v2, 0xbfb8aa3b, v67
	v_exp_f32_e32 v2, v2
	s_nop 0
	v_add_f32_e32 v2, 1.0, v2
	v_rcp_f32_e32 v2, v2
	s_nop 0
	v_fmac_f32_e32 v63, v2, v0
	v_cvt_pk_bf16_f32 v0, v63, s0
	v_mad_i64_i32 v[62:63], s[14:15], v59, s61, v[20:21]
	global_store_short v[62:63], v0, off
	v_add_f32_e32 v0, v3, v1
	v_mul_f32_e32 v1, 0xbfb8aa3b, v73
	v_exp_f32_e32 v1, v1
	s_nop 0
	v_add_f32_e32 v1, 1.0, v1
	v_rcp_f32_e32 v1, v1
	s_nop 0
	v_fmac_f32_e32 v72, v1, v0
	v_cvt_pk_bf16_f32 v2, v72, s0
	v_mad_i64_i32 v[0:1], s[14:15], v70, s61, v[20:21]
	global_store_short v[0:1], v2, off
	v_mul_f32_e32 v2, 0xbfb8aa3b, v58
	v_exp_f32_e32 v2, v2
	ds_read2st64_b32 v[0:1], v23 offset0:4 offset1:5
	v_add_f32_e32 v2, 1.0, v2
	v_rcp_f32_e32 v2, v2
	s_waitcnt lgkmcnt(0)
	v_add_f32_e32 v0, v4, v0
	v_fmac_f32_e32 v57, v2, v0
	v_cvt_pk_bf16_f32 v0, v57, s0
	v_mad_i64_i32 v[2:3], s[14:15], v56, s61, v[20:21]
	global_store_short v[2:3], v0, off
	v_add_f32_e32 v0, v5, v1
	v_mul_f32_e32 v1, 0xbfb8aa3b, v68
	v_exp_f32_e32 v1, v1
	s_nop 0
	v_add_f32_e32 v1, 1.0, v1
	v_rcp_f32_e32 v1, v1
	s_nop 0
	v_fmac_f32_e32 v64, v1, v0
	v_cvt_pk_bf16_f32 v2, v64, s0
	v_mad_i64_i32 v[0:1], s[14:15], v60, s61, v[20:21]
	global_store_short v[0:1], v2, off
	v_mul_f32_e32 v2, 0xbfb8aa3b, v54
	v_exp_f32_e32 v2, v2
	ds_read2st64_b32 v[0:1], v23 offset0:6 offset1:7
	v_add_f32_e32 v2, 1.0, v2
	v_rcp_f32_e32 v2, v2
	s_waitcnt lgkmcnt(0)
	v_add_f32_e32 v0, v6, v0
	v_fmac_f32_e32 v51, v2, v0
	v_cvt_pk_bf16_f32 v0, v51, s0
	v_mad_i64_i32 v[2:3], s[14:15], v50, s61, v[20:21]
	global_store_short v[2:3], v0, off
	v_add_f32_e32 v0, v7, v1
	v_mul_f32_e32 v1, 0xbfb8aa3b, v55
	v_exp_f32_e32 v1, v1
	s_nop 0
	v_add_f32_e32 v1, 1.0, v1
	v_rcp_f32_e32 v1, v1
	s_nop 0
	v_fmac_f32_e32 v49, v1, v0
	v_cvt_pk_bf16_f32 v2, v49, s0
	v_mad_i64_i32 v[0:1], s[14:15], v38, s61, v[20:21]
	global_store_short v[0:1], v2, off
	v_mul_f32_e32 v2, 0xbfb8aa3b, v48
	v_exp_f32_e32 v2, v2
	ds_read2st64_b32 v[0:1], v23 offset0:8 offset1:9
	v_add_f32_e32 v2, 1.0, v2
	v_rcp_f32_e32 v2, v2
	s_waitcnt lgkmcnt(0)
	v_add_f32_e32 v0, v8, v0
	v_fmac_f32_e32 v43, v2, v0
	v_cvt_pk_bf16_f32 v0, v43, s0
	v_mad_i64_i32 v[2:3], s[14:15], v39, s61, v[20:21]
	global_store_short v[2:3], v0, off
	v_add_f32_e32 v0, v9, v1
	v_mul_f32_e32 v1, 0xbfb8aa3b, v46
	v_exp_f32_e32 v1, v1
	s_nop 0
	v_add_f32_e32 v1, 1.0, v1
	v_rcp_f32_e32 v1, v1
	s_nop 0
	v_fmac_f32_e32 v42, v1, v0
	v_cvt_pk_bf16_f32 v2, v42, s0
	v_mad_i64_i32 v[0:1], s[14:15], v37, s61, v[20:21]
	global_store_short v[0:1], v2, off
	v_mul_f32_e32 v2, 0xbfb8aa3b, v44
	v_exp_f32_e32 v2, v2
	ds_read2st64_b32 v[0:1], v23 offset0:10 offset1:11
	v_add_f32_e32 v2, 1.0, v2
	v_rcp_f32_e32 v2, v2
	s_waitcnt lgkmcnt(0)
	v_add_f32_e32 v0, v10, v0
	v_fmac_f32_e32 v40, v2, v0
	v_cvt_pk_bf16_f32 v0, v40, s0
	v_mad_i64_i32 v[2:3], s[14:15], v35, s61, v[20:21]
	global_store_short v[2:3], v0, off
	v_add_f32_e32 v0, v11, v1
	v_mul_f32_e32 v1, 0xbfb8aa3b, v53
	v_exp_f32_e32 v1, v1
	s_nop 0
	v_add_f32_e32 v1, 1.0, v1
	v_rcp_f32_e32 v1, v1
	s_nop 0
	v_fmac_f32_e32 v52, v1, v0
	v_cvt_pk_bf16_f32 v2, v52, s0
	v_mad_i64_i32 v[0:1], s[14:15], v47, s61, v[20:21]
	global_store_short v[0:1], v2, off
	v_mul_f32_e32 v2, 0xbfb8aa3b, v34
	v_exp_f32_e32 v2, v2
	ds_read2st64_b32 v[0:1], v23 offset0:12 offset1:13
	v_add_f32_e32 v2, 1.0, v2
	v_rcp_f32_e32 v2, v2
	s_waitcnt lgkmcnt(0)
	v_add_f32_e32 v0, v12, v0
	v_fmac_f32_e32 v33, v2, v0
	v_cvt_pk_bf16_f32 v0, v33, s0
	v_mad_i64_i32 v[2:3], s[14:15], v32, s61, v[20:21]
	global_store_short v[2:3], v0, off
	v_add_f32_e32 v0, v13, v1
	v_mul_f32_e32 v1, 0xbfb8aa3b, v45
	v_exp_f32_e32 v1, v1
	s_nop 0
	v_add_f32_e32 v1, 1.0, v1
	v_rcp_f32_e32 v1, v1
	s_nop 0
	v_fmac_f32_e32 v41, v1, v0
	v_cvt_pk_bf16_f32 v2, v41, s0
	v_mad_i64_i32 v[0:1], s[14:15], v36, s61, v[20:21]
	global_store_short v[0:1], v2, off
	v_mul_f32_e32 v2, 0xbfb8aa3b, v30
	v_exp_f32_e32 v2, v2
	ds_read2st64_b32 v[0:1], v23 offset0:14 offset1:15
	v_add_f32_e32 v2, 1.0, v2
	v_rcp_f32_e32 v2, v2
	s_waitcnt lgkmcnt(0)
	v_add_f32_e32 v0, v14, v0
	v_fmac_f32_e32 v29, v2, v0
	v_cvt_pk_bf16_f32 v0, v29, s0
	v_mad_i64_i32 v[2:3], s[14:15], v28, s61, v[20:21]
	global_store_short v[2:3], v0, off
	v_add_f32_e32 v0, v15, v1
	v_mul_f32_e32 v1, 0xbfb8aa3b, v31
	v_exp_f32_e32 v1, v1
	s_nop 0
	v_add_f32_e32 v1, 1.0, v1
	v_rcp_f32_e32 v1, v1
	s_nop 0
	v_fmac_f32_e32 v27, v1, v0
	v_cvt_pk_bf16_f32 v2, v27, s0
	v_mad_i64_i32 v[0:1], s[14:15], v26, s61, v[20:21]
	global_store_short v[0:1], v2, off
	s_branch .LBB0_1070
